# P2: unaligned epilogues (leading half no longer waits for the trailing half's last MFMA block; extra barrier for it at the phase exit)
# baseline (speedup 1.0000x reference)
; DEV u32x4 pack8(const float (&f)[8]) { u32x4 w; w.x = cvt_pk_bf16(f[0], f[1]); w.y = cvt_pk_bf16(f[2], f[3]); w.z = cvt_pk_bf16(f[4], f[5]); w.w = cvt_pk_bf16(f[6], f[7]); return w; }
; DEV float silu_f(float x) { return x * __builtin_amdgcn_rcpf(1.f + __expf(-x)); }
;     DEV void operator()(const f32x4 (&acc)[2][2][4][2], const Unit& u, int wr, int wc, int fr, int fq) const {
;         asm volatile("" : "+v"(fr), "+v"(fq));
;         const int row0 = u.pm * 256 + wr * 64 + fr, col0 = u.pn * 128 + wc * 32 + 8 * fq;
;         f32x4 sg[2], su[2];
;         if (FUSED) { const int b = u.pm >> 4; const float* sp = shw + (size_t)b * NFF2 + u.pn * 256 + wc * 32 + 8 * fq;
;             sg[0] = *(const f32x4*)sp; sg[1] = *(const f32x4*)(sp + 4); su[0] = *(const f32x4*)(sp + 128); su[1] = *(const f32x4*)(sp + 132); }
;         float rstd8[8];
;         if (FUSED) row_rstd8(rs, row0, fq, rstd8);
; #pragma unroll
;         for (int ai = 0; ai < 2; ++ai)
; #pragma unroll
;             for (int m = 0; m < 4; ++m) {
;                 const int row = row0 + ai * 128 + m * 16;
;                 const float rstd = FUSED ? rstd8[ai * 4 + m] : 1.f;
;                 float h[8];
; #pragma unroll
;                 for (int n = 0; n < 2; ++n)
; #pragma unroll
;                     for (int j = 0; j < 4; ++j) { float g = acc[ai][0][m][n][j], up = acc[ai][1][m][n][j]; if (FUSED) { g = g * rstd + sg[n][j]; up = up * rstd + su[n][j]; } h[4 * n + j] = silu_f(g) * up; }
;                 *(u32x4*)(H + (size_t)row * DFF + col0) = pack8(h);
;             }
.LBB0_295:
	v_mul_f32_e32 v155, 0xbfb8aa3b, v126
	v_exp_f32_e32 v155, v155
	v_mul_f32_e32 v156, 0xbfb8aa3b, v127
	v_exp_f32_e32 v157, v156
	v_mov_b32_e32 v153, v147
	v_add_f32_e32 v155, 1.0, v155
	v_rcp_f32_e32 v156, v155
	v_add_f32_e32 v155, 1.0, v157
	v_rcp_f32_e32 v157, v155
	v_mov_b32_e32 v154, v148
	s_lshl_b32 s27, s62, 7
	v_pk_mul_f32 v[126:127], v[126:127], v[156:157]
	v_mul_f32_e32 v156, 0xbfb8aa3b, v128
	v_mul_f32_e32 v157, 0xbfb8aa3b, v129
	v_exp_f32_e32 v156, v156
	v_exp_f32_e32 v157, v157
	v_pk_mul_f32 v[118:119], v[126:127], v[118:119]
	s_lshl_b32 s25, s34, 8
	v_add_f32_e32 v126, 1.0, v156
	v_add_f32_e32 v127, 1.0, v157
	v_mul_f32_e32 v156, 0xbfb8aa3b, v122
	v_mul_f32_e32 v157, 0xbfb8aa3b, v123
	v_rcp_f32_e32 v126, v126
	v_rcp_f32_e32 v127, v127
	v_exp_f32_e32 v156, v156
	v_exp_f32_e32 v157, v157
	v_cvt_pk_bf16_f32 v118, v118, v119
	v_pk_mul_f32 v[126:127], v[128:129], v[126:127]
	v_add_f32_e32 v128, 1.0, v156
	v_add_f32_e32 v129, 1.0, v157
	v_mul_f32_e32 v156, 0xbfb8aa3b, v124
	v_mul_f32_e32 v157, 0xbfb8aa3b, v125
	v_exp_f32_e32 v156, v156
	v_exp_f32_e32 v157, v157
	v_rcp_f32_e32 v128, v128
	v_rcp_f32_e32 v129, v129
	v_add_f32_e32 v156, 1.0, v156
	v_add_f32_e32 v157, 1.0, v157
	v_rcp_f32_e32 v156, v156
	v_rcp_f32_e32 v157, v157
	v_pk_mul_f32 v[122:123], v[122:123], v[128:129]
	v_pk_mul_f32 v[120:121], v[126:127], v[120:121]
	v_pk_mul_f32 v[114:115], v[122:123], v[114:115]
	v_pk_mul_f32 v[122:123], v[124:125], v[156:157]
	v_cvt_pk_bf16_f32 v119, v120, v121
	v_pk_mul_f32 v[116:117], v[122:123], v[116:117]
	s_or_b32 s27, s27, s51
	v_cvt_pk_bf16_f32 v121, v116, v117
	v_mul_f32_e32 v116, 0xbfb8aa3b, v110
	v_exp_f32_e32 v116, v116
	v_mul_f32_e32 v117, 0xbfb8aa3b, v111
	v_exp_f32_e32 v117, v117
	v_lshl_add_u32 v154, v154, 3, s27
	s_add_i32 s25, s25, s49
	v_add_f32_e32 v116, 1.0, v116
	v_add_u32_e32 v153, s25, v153
	v_ashrrev_i32_e32 v155, 31, v154
	v_cvt_pk_bf16_f32 v120, v114, v115
	v_mov_b64_e32 v[114:115], s[56:57]
	v_rcp_f32_e32 v124, v116
	v_add_f32_e32 v116, 1.0, v117
	v_mad_i64_i32 v[122:123], s[36:37], v153, s59, v[114:115]
	v_rcp_f32_e32 v125, v116
	v_lshlrev_b64 v[116:117], 1, v[154:155]
	v_lshl_add_u64 v[122:123], v[122:123], 0, v[116:117]
	global_store_dwordx4 v[122:123], v[118:121], off
	v_pk_mul_f32 v[110:111], v[110:111], v[124:125]
	s_andn2_b64 vcc, exec, s[4:5]
	v_mul_f32_e32 v118, 0xbfb8aa3b, v112
	v_mul_f32_e32 v119, 0xbfb8aa3b, v113
	v_exp_f32_e32 v118, v118
	v_exp_f32_e32 v119, v119
	v_pk_mul_f32 v[102:103], v[110:111], v[102:103]
	s_mov_b64 s[4:5], -1
	v_add_f32_e32 v110, 1.0, v118
	v_add_f32_e32 v111, 1.0, v119
	v_mul_f32_e32 v118, 0xbfb8aa3b, v106
	v_mul_f32_e32 v119, 0xbfb8aa3b, v107
	v_rcp_f32_e32 v110, v110
	v_rcp_f32_e32 v111, v111
	v_exp_f32_e32 v118, v118
	v_exp_f32_e32 v119, v119
	v_pk_mul_f32 v[110:111], v[112:113], v[110:111]
	v_add_f32_e32 v112, 1.0, v118
	v_add_f32_e32 v113, 1.0, v119
	v_mul_f32_e32 v118, 0xbfb8aa3b, v108
	v_mul_f32_e32 v119, 0xbfb8aa3b, v109
	v_exp_f32_e32 v118, v118
	v_exp_f32_e32 v119, v119
	v_rcp_f32_e32 v112, v112
	v_rcp_f32_e32 v113, v113
	v_add_f32_e32 v118, 1.0, v118
	v_add_f32_e32 v119, 1.0, v119
	v_rcp_f32_e32 v118, v118
	v_rcp_f32_e32 v119, v119
	v_pk_mul_f32 v[106:107], v[106:107], v[112:113]
	v_pk_mul_f32 v[104:105], v[110:111], v[104:105]
	v_pk_mul_f32 v[106:107], v[106:107], v[98:99]
	v_pk_mul_f32 v[98:99], v[108:109], v[118:119]
	v_add_u32_e32 v110, 16, v153
	v_pk_mul_f32 v[108:109], v[98:99], v[100:101]
	v_mul_f32_e32 v101, 0xbfb8aa3b, v94
	v_cvt_pk_bf16_f32 v98, v102, v103
	v_exp_f32_e32 v102, v101
	v_mul_f32_e32 v101, 0xbfb8aa3b, v95
	v_exp_f32_e32 v103, v101
	v_cvt_pk_bf16_f32 v99, v104, v105
	v_mad_i64_i32 v[104:105], s[36:37], v110, s59, v[114:115]
	v_cvt_pk_bf16_f32 v100, v106, v107
	v_cvt_pk_bf16_f32 v101, v108, v109
	v_add_f32_e32 v102, 1.0, v102
	v_add_f32_e32 v103, 1.0, v103
	v_lshl_add_u64 v[104:105], v[104:105], 0, v[116:117]
	v_rcp_f32_e32 v102, v102
	v_rcp_f32_e32 v103, v103
	global_store_dwordx4 v[104:105], v[98:101], off
	v_pk_mul_f32 v[94:95], v[94:95], v[102:103]
	s_nop 0
	v_mul_f32_e32 v98, 0xbfb8aa3b, v96
	v_mul_f32_e32 v99, 0xbfb8aa3b, v97
	v_exp_f32_e32 v98, v98
	v_exp_f32_e32 v99, v99
	v_pk_mul_f32 v[86:87], v[94:95], v[86:87]
	v_add_f32_e32 v94, 1.0, v98
	v_add_f32_e32 v95, 1.0, v99
	v_mul_f32_e32 v98, 0xbfb8aa3b, v90
	v_mul_f32_e32 v99, 0xbfb8aa3b, v91
	v_rcp_f32_e32 v94, v94
	v_rcp_f32_e32 v95, v95
	v_exp_f32_e32 v98, v98
	v_exp_f32_e32 v99, v99
	v_pk_mul_f32 v[94:95], v[96:97], v[94:95]
	v_add_f32_e32 v96, 1.0, v98
	v_add_f32_e32 v97, 1.0, v99
	v_mul_f32_e32 v98, 0xbfb8aa3b, v92
	v_mul_f32_e32 v99, 0xbfb8aa3b, v93
	v_exp_f32_e32 v98, v98
	v_exp_f32_e32 v99, v99
	v_rcp_f32_e32 v96, v96
	v_rcp_f32_e32 v97, v97
	v_add_f32_e32 v98, 1.0, v98
	v_add_f32_e32 v99, 1.0, v99
	v_rcp_f32_e32 v98, v98
	v_rcp_f32_e32 v99, v99
	v_pk_mul_f32 v[90:91], v[90:91], v[96:97]
	v_pk_mul_f32 v[88:89], v[94:95], v[88:89]
	v_pk_mul_f32 v[90:91], v[90:91], v[82:83]
	v_pk_mul_f32 v[82:83], v[92:93], v[98:99]
	v_add_u32_e32 v94, 32, v153
	v_pk_mul_f32 v[92:93], v[82:83], v[84:85]
	v_mul_f32_e32 v85, 0xbfb8aa3b, v78
	v_cvt_pk_bf16_f32 v82, v86, v87
	v_exp_f32_e32 v86, v85
	v_mul_f32_e32 v85, 0xbfb8aa3b, v79
	v_exp_f32_e32 v87, v85
	v_cvt_pk_bf16_f32 v83, v88, v89
	v_mad_i64_i32 v[88:89], s[36:37], v94, s59, v[114:115]
	v_cvt_pk_bf16_f32 v84, v90, v91
	v_cvt_pk_bf16_f32 v85, v92, v93
	v_add_f32_e32 v86, 1.0, v86
	v_add_f32_e32 v87, 1.0, v87
	v_lshl_add_u64 v[88:89], v[88:89], 0, v[116:117]
	v_rcp_f32_e32 v86, v86
	v_rcp_f32_e32 v87, v87
	global_store_dwordx4 v[88:89], v[82:85], off
	v_pk_mul_f32 v[78:79], v[78:79], v[86:87]
	s_nop 0
	v_mul_f32_e32 v82, 0xbfb8aa3b, v80
; DEV float silu_f(float x) { return x * __builtin_amdgcn_rcpf(1.f + __expf(-x)); }
; DEV u32x4 pack8(const float (&f)[8]) { u32x4 w; w.x = cvt_pk_bf16(f[0], f[1]); w.y = cvt_pk_bf16(f[2], f[3]); w.z = cvt_pk_bf16(f[4], f[5]); w.w = cvt_pk_bf16(f[6], f[7]); return w; }
;     DEV void operator()(const f32x4 (&acc)[2][2][4][2], const Unit& u, int wr, int wc, int fr, int fq) const {
;     ...
;         for (int ai = 0; ai < 2; ++ai)
; #pragma unroll
;             for (int m = 0; m < 4; ++m) {
;                 const int row = row0 + ai * 128 + m * 16;
;                 const float rstd = FUSED ? rstd8[ai * 4 + m] : 1.f;
;                 float h[8];
; #pragma unroll
;                 for (int n = 0; n < 2; ++n)
; #pragma unroll
;                     for (int j = 0; j < 4; ++j) { float g = acc[ai][0][m][n][j], up = acc[ai][1][m][n][j]; if (FUSED) { g = g * rstd + sg[n][j]; up = up * rstd + su[n][j]; } h[4 * n + j] = silu_f(g) * up; }
;                 *(u32x4*)(H + (size_t)row * DFF + col0) = pack8(h);
;             }
	v_mul_f32_e32 v83, 0xbfb8aa3b, v81
	v_exp_f32_e32 v82, v82
	v_exp_f32_e32 v83, v83
	v_pk_mul_f32 v[70:71], v[78:79], v[70:71]
	v_add_f32_e32 v78, 1.0, v82
	v_add_f32_e32 v79, 1.0, v83
	v_mul_f32_e32 v82, 0xbfb8aa3b, v74
	v_mul_f32_e32 v83, 0xbfb8aa3b, v75
	v_rcp_f32_e32 v78, v78
	v_rcp_f32_e32 v79, v79
	v_exp_f32_e32 v82, v82
	v_exp_f32_e32 v83, v83
	v_pk_mul_f32 v[78:79], v[80:81], v[78:79]
	v_add_f32_e32 v80, 1.0, v82
	v_add_f32_e32 v81, 1.0, v83
	v_mul_f32_e32 v82, 0xbfb8aa3b, v76
	v_mul_f32_e32 v83, 0xbfb8aa3b, v77
	v_exp_f32_e32 v82, v82
	v_exp_f32_e32 v83, v83
	v_rcp_f32_e32 v80, v80
	v_rcp_f32_e32 v81, v81
	v_add_f32_e32 v82, 1.0, v82
	v_add_f32_e32 v83, 1.0, v83
	v_rcp_f32_e32 v82, v82
	v_rcp_f32_e32 v83, v83
	v_pk_mul_f32 v[74:75], v[74:75], v[80:81]
	v_pk_mul_f32 v[72:73], v[78:79], v[72:73]
	v_pk_mul_f32 v[74:75], v[74:75], v[66:67]
	v_pk_mul_f32 v[66:67], v[76:77], v[82:83]
	v_add_u32_e32 v78, 48, v153
	v_pk_mul_f32 v[76:77], v[66:67], v[68:69]
	v_cvt_pk_bf16_f32 v66, v70, v71
	v_mul_f32_e32 v70, 0xbfb8aa3b, v62
	v_cvt_pk_bf16_f32 v67, v72, v73
	v_exp_f32_e32 v72, v70
	v_mul_f32_e32 v70, 0xbfb8aa3b, v63
	v_exp_f32_e32 v73, v70
	v_mad_i64_i32 v[70:71], s[36:37], v78, s59, v[114:115]
	v_cvt_pk_bf16_f32 v68, v74, v75
	v_cvt_pk_bf16_f32 v69, v76, v77
	v_add_f32_e32 v72, 1.0, v72
	v_add_f32_e32 v73, 1.0, v73
	v_lshl_add_u64 v[70:71], v[70:71], 0, v[116:117]
	v_rcp_f32_e32 v72, v72
	v_rcp_f32_e32 v73, v73
	global_store_dwordx4 v[70:71], v[66:69], off
	v_pk_mul_f32 v[62:63], v[62:63], v[72:73]
	s_nop 0
	v_mul_f32_e32 v66, 0xbfb8aa3b, v64
	v_mul_f32_e32 v67, 0xbfb8aa3b, v65
	v_exp_f32_e32 v66, v66
	v_exp_f32_e32 v67, v67
	v_pk_mul_f32 v[54:55], v[62:63], v[54:55]
	v_add_u32_e32 v68, 0x80, v153
	v_add_f32_e32 v62, 1.0, v66
	v_add_f32_e32 v63, 1.0, v67
	v_mul_f32_e32 v66, 0xbfb8aa3b, v58
	v_mul_f32_e32 v67, 0xbfb8aa3b, v59
	v_rcp_f32_e32 v62, v62
	v_rcp_f32_e32 v63, v63
	v_exp_f32_e32 v66, v66
	v_exp_f32_e32 v67, v67
	v_pk_mul_f32 v[62:63], v[64:65], v[62:63]
	v_add_f32_e32 v64, 1.0, v66
	v_add_f32_e32 v65, 1.0, v67
	v_mul_f32_e32 v66, 0xbfb8aa3b, v60
	v_mul_f32_e32 v67, 0xbfb8aa3b, v61
	v_exp_f32_e32 v66, v66
	v_exp_f32_e32 v67, v67
	v_rcp_f32_e32 v64, v64
	v_rcp_f32_e32 v65, v65
	v_add_f32_e32 v66, 1.0, v66
	v_add_f32_e32 v67, 1.0, v67
	v_rcp_f32_e32 v66, v66
	v_rcp_f32_e32 v67, v67
	v_pk_mul_f32 v[58:59], v[58:59], v[64:65]
	v_pk_mul_f32 v[56:57], v[62:63], v[56:57]
	v_pk_mul_f32 v[58:59], v[58:59], v[50:51]
	v_pk_mul_f32 v[50:51], v[60:61], v[66:67]
	s_nop 0
	v_pk_mul_f32 v[60:61], v[50:51], v[52:53]
	v_mul_f32_e32 v53, 0xbfb8aa3b, v46
	v_cvt_pk_bf16_f32 v50, v54, v55
	v_exp_f32_e32 v54, v53
	v_mul_f32_e32 v53, 0xbfb8aa3b, v47
	v_exp_f32_e32 v55, v53
	v_cvt_pk_bf16_f32 v51, v56, v57
	v_mad_i64_i32 v[56:57], s[36:37], v68, s59, v[114:115]
	v_cvt_pk_bf16_f32 v52, v58, v59
	v_cvt_pk_bf16_f32 v53, v60, v61
	v_add_f32_e32 v54, 1.0, v54
	v_add_f32_e32 v55, 1.0, v55
	v_lshl_add_u64 v[56:57], v[56:57], 0, v[116:117]
	v_rcp_f32_e32 v54, v54
	v_rcp_f32_e32 v55, v55
	global_store_dwordx4 v[56:57], v[50:53], off
	v_pk_mul_f32 v[46:47], v[46:47], v[54:55]
	s_nop 0
	v_mul_f32_e32 v50, 0xbfb8aa3b, v48
	v_mul_f32_e32 v51, 0xbfb8aa3b, v49
	v_exp_f32_e32 v50, v50
	v_exp_f32_e32 v51, v51
	v_pk_mul_f32 v[38:39], v[46:47], v[38:39]
	v_add_f32_e32 v46, 1.0, v50
	v_add_f32_e32 v47, 1.0, v51
	v_mul_f32_e32 v50, 0xbfb8aa3b, v42
	v_mul_f32_e32 v51, 0xbfb8aa3b, v43
	v_rcp_f32_e32 v46, v46
	v_rcp_f32_e32 v47, v47
	v_exp_f32_e32 v50, v50
	v_exp_f32_e32 v51, v51
	v_pk_mul_f32 v[46:47], v[48:49], v[46:47]
	v_add_f32_e32 v48, 1.0, v50
	v_add_f32_e32 v49, 1.0, v51
	v_mul_f32_e32 v50, 0xbfb8aa3b, v44
	v_mul_f32_e32 v51, 0xbfb8aa3b, v45
	v_exp_f32_e32 v50, v50
	v_exp_f32_e32 v51, v51
	v_rcp_f32_e32 v48, v48
	v_rcp_f32_e32 v49, v49
	v_add_f32_e32 v50, 1.0, v50
	v_add_f32_e32 v51, 1.0, v51
	v_rcp_f32_e32 v50, v50
; #define PG8_WAIT_V(n) asm volatile("s_waitcnt vmcnt(" #n ")" ::: "memory")
; #define PG8_BAR __builtin_amdgcn_s_barrier()
; DEV float silu_f(float x) { return x * __builtin_amdgcn_rcpf(1.f + __expf(-x)); }
; DEV u32x4 pack8(const float (&f)[8]) { u32x4 w; w.x = cvt_pk_bf16(f[0], f[1]); w.y = cvt_pk_bf16(f[2], f[3]); w.z = cvt_pk_bf16(f[4], f[5]); w.w = cvt_pk_bf16(f[6], f[7]); return w; }
; template <class Epi, class Sched, bool ALIGN_EPI = false, bool SP2 = false>
; __device__ __forceinline__ void gemm_phase(PG8_LAS unsigned char* lds, const Gemm g, const Sched& S, const Epi& E) {
;     ...
;         if constexpr (ALIGN_EPI) { if (wr == 0) PG8_BAR; }
;         if constexpr (!Epi::AFTER_DRAIN) { E(acc, cur, wr, wc, fr, fq); S.done(cur); }
;         if (!has_next) break;
; #pragma unroll
;         for (int a = 0; a < 2; ++a)
; #pragma unroll
;             for (int b = 0; b < 2; ++b)
; #pragma unroll
;                 for (int m = 0; m < 4; ++m)
; #pragma unroll
;                     for (int n = 0; n < 2; ++n) acc[a][b][m][n] = (f32x4){0.f, 0.f, 0.f, 0.f};
;         cur = nxt; cA = nA; cB = nB; ++ui;
;         if constexpr (ALIGN_EPI) { if (wr == 1) PG8_BAR; }
;     }
;     PG8_WAIT_V(0);
;     if constexpr (!ALIGN_EPI) { if (wr == 0) PG8_BAR; }
;     DEV void operator()(const f32x4 (&acc)[2][2][4][2], const Unit& u, int wr, int wc, int fr, int fq) const {
;     ...
;         for (int ai = 0; ai < 2; ++ai)
; #pragma unroll
;             for (int m = 0; m < 4; ++m) {
;                 const int row = row0 + ai * 128 + m * 16;
;                 const float rstd = FUSED ? rstd8[ai * 4 + m] : 1.f;
;                 float h[8];
; #pragma unroll
;                 for (int n = 0; n < 2; ++n)
; #pragma unroll
;                     for (int j = 0; j < 4; ++j) { float g = acc[ai][0][m][n][j], up = acc[ai][1][m][n][j]; if (FUSED) { g = g * rstd + sg[n][j]; up = up * rstd + su[n][j]; } h[4 * n + j] = silu_f(g) * up; }
;                 *(u32x4*)(H + (size_t)row * DFF + col0) = pack8(h);
;             }
	v_rcp_f32_e32 v51, v51
	v_pk_mul_f32 v[42:43], v[42:43], v[48:49]
	v_pk_mul_f32 v[40:41], v[46:47], v[40:41]
	v_pk_mul_f32 v[42:43], v[42:43], v[34:35]
	v_pk_mul_f32 v[34:35], v[44:45], v[50:51]
	v_add_u32_e32 v46, 0x90, v153
	v_pk_mul_f32 v[44:45], v[34:35], v[36:37]
	v_mul_f32_e32 v37, 0xbfb8aa3b, v30
	v_cvt_pk_bf16_f32 v34, v38, v39
	v_exp_f32_e32 v38, v37
	v_mul_f32_e32 v37, 0xbfb8aa3b, v31
	v_exp_f32_e32 v39, v37
	v_cvt_pk_bf16_f32 v35, v40, v41
	v_mad_i64_i32 v[40:41], s[36:37], v46, s59, v[114:115]
	v_cvt_pk_bf16_f32 v36, v42, v43
	v_cvt_pk_bf16_f32 v37, v44, v45
	v_add_f32_e32 v38, 1.0, v38
	v_add_f32_e32 v39, 1.0, v39
	v_lshl_add_u64 v[40:41], v[40:41], 0, v[116:117]
	v_rcp_f32_e32 v38, v38
	v_rcp_f32_e32 v39, v39
	global_store_dwordx4 v[40:41], v[34:37], off
	v_pk_mul_f32 v[30:31], v[30:31], v[38:39]
	s_nop 0
	v_mul_f32_e32 v34, 0xbfb8aa3b, v32
	v_mul_f32_e32 v35, 0xbfb8aa3b, v33
	v_exp_f32_e32 v34, v34
	v_exp_f32_e32 v35, v35
	v_pk_mul_f32 v[22:23], v[30:31], v[22:23]
	v_add_f32_e32 v30, 1.0, v34
	v_add_f32_e32 v31, 1.0, v35
	v_mul_f32_e32 v34, 0xbfb8aa3b, v26
	v_mul_f32_e32 v35, 0xbfb8aa3b, v27
	v_rcp_f32_e32 v30, v30
	v_rcp_f32_e32 v31, v31
	v_exp_f32_e32 v34, v34
	v_exp_f32_e32 v35, v35
	v_pk_mul_f32 v[30:31], v[32:33], v[30:31]
	v_add_f32_e32 v32, 1.0, v34
	v_add_f32_e32 v33, 1.0, v35
	v_mul_f32_e32 v34, 0xbfb8aa3b, v28
	v_mul_f32_e32 v35, 0xbfb8aa3b, v29
	v_exp_f32_e32 v34, v34
	v_exp_f32_e32 v35, v35
	v_rcp_f32_e32 v32, v32
	v_rcp_f32_e32 v33, v33
	v_add_f32_e32 v34, 1.0, v34
	v_add_f32_e32 v35, 1.0, v35
	v_rcp_f32_e32 v34, v34
	v_rcp_f32_e32 v35, v35
	v_pk_mul_f32 v[26:27], v[26:27], v[32:33]
	v_pk_mul_f32 v[24:25], v[30:31], v[24:25]
	v_pk_mul_f32 v[26:27], v[26:27], v[18:19]
	v_pk_mul_f32 v[18:19], v[28:29], v[34:35]
	v_add_u32_e32 v30, 0xa0, v153
	v_pk_mul_f32 v[28:29], v[18:19], v[20:21]
	v_mul_f32_e32 v21, 0xbfb8aa3b, v14
	v_cvt_pk_bf16_f32 v18, v22, v23
	v_exp_f32_e32 v22, v21
	v_mul_f32_e32 v21, 0xbfb8aa3b, v15
	v_exp_f32_e32 v23, v21
	v_cvt_pk_bf16_f32 v19, v24, v25
	v_mad_i64_i32 v[24:25], s[36:37], v30, s59, v[114:115]
	v_cvt_pk_bf16_f32 v20, v26, v27
	v_cvt_pk_bf16_f32 v21, v28, v29
	v_add_f32_e32 v22, 1.0, v22
	v_add_f32_e32 v23, 1.0, v23
	v_lshl_add_u64 v[24:25], v[24:25], 0, v[116:117]
	v_rcp_f32_e32 v22, v22
	v_rcp_f32_e32 v23, v23
	global_store_dwordx4 v[24:25], v[18:21], off
	v_pk_mul_f32 v[14:15], v[14:15], v[22:23]
	s_nop 0
	v_mul_f32_e32 v18, 0xbfb8aa3b, v16
	v_mul_f32_e32 v19, 0xbfb8aa3b, v17
	v_exp_f32_e32 v18, v18
	v_exp_f32_e32 v19, v19
	v_pk_mul_f32 v[6:7], v[14:15], v[6:7]
	v_add_f32_e32 v14, 1.0, v18
	v_add_f32_e32 v15, 1.0, v19
	v_mul_f32_e32 v18, 0xbfb8aa3b, v10
	v_mul_f32_e32 v19, 0xbfb8aa3b, v11
	v_rcp_f32_e32 v14, v14
	v_rcp_f32_e32 v15, v15
	v_exp_f32_e32 v18, v18
	v_exp_f32_e32 v19, v19
	v_pk_mul_f32 v[14:15], v[16:17], v[14:15]
	v_add_f32_e32 v16, 1.0, v18
	v_add_f32_e32 v17, 1.0, v19
	v_mul_f32_e32 v18, 0xbfb8aa3b, v12
	v_mul_f32_e32 v19, 0xbfb8aa3b, v13
	v_exp_f32_e32 v18, v18
	v_exp_f32_e32 v19, v19
	v_rcp_f32_e32 v16, v16
	v_rcp_f32_e32 v17, v17
	v_add_f32_e32 v18, 1.0, v18
	v_add_f32_e32 v19, 1.0, v19
	v_rcp_f32_e32 v18, v18
	v_rcp_f32_e32 v19, v19
	v_pk_mul_f32 v[10:11], v[10:11], v[16:17]
	v_pk_mul_f32 v[8:9], v[14:15], v[8:9]
	v_pk_mul_f32 v[10:11], v[10:11], v[2:3]
	v_pk_mul_f32 v[2:3], v[12:13], v[18:19]
	v_add_u32_e32 v14, 0xb0, v153
	v_pk_mul_f32 v[12:13], v[2:3], v[4:5]
	v_cvt_pk_bf16_f32 v2, v6, v7
	v_mad_i64_i32 v[6:7], s[36:37], v14, s59, v[114:115]
	v_cvt_pk_bf16_f32 v3, v8, v9
	v_cvt_pk_bf16_f32 v4, v10, v11
	v_cvt_pk_bf16_f32 v5, v12, v13
	v_lshl_add_u64 v[6:7], v[6:7], 0, v[116:117]
	global_store_dwordx4 v[6:7], v[2:5], off
	s_cbranch_vccnz .LBB0_288
	s_andn2_b64 vcc, exec, s[6:7]
	s_cbranch_vccnz .LBB0_287
	s_branch .LBB0_287
.LBB0_298:
	s_and_b64 vcc, exec, s[12:13]
	s_cbranch_vccz .Lp2_noextra
	s_barrier
